# plus diff attention: far tiles start the QK^T accumulation from the shared bias/reference block through the MFMA C operand instead of copying it into both score blocks first (16 v_mov_b64 per tile rem
# speedup vs baseline: 1.0077x; 1.0010x over previous
; __device__ __forceinline__ int crow(int r, int hi) { return (r & 3) + 8 * (r >> 2) + 4 * hi; }
; template <int MODE>
; __device__ __forceinline__ void attn_unit(const AttnP& P, int b, int h, int u, int j0, char* lds, float lam) {
;     ...
;       const bool far = (MODE == 0) && (j * 64 + 63 <= qw - 128);
;       if (far) { p0 = negm; p1 = negm; }
;       else if (MODE == 0) { const int idx0 = j * 64 - (qw + r32) + 255;
; #pragma unroll
;         for (int r = 0; r < 16; ++r) { p0[r] = lut[idx0 + crow(r, hi)] - mref; p1[r] = lut[idx0 + 32 + crow(r, hi)] - mref; }
;       } else {
; #pragma unroll
;         for (int r = 0; r < 16; ++r) { p0[r] = Gl[j * 64 + crow(r, hi)] - mref; p1[r] = Gl[j * 64 + 32 + crow(r, hi)] - mref; }
;       }
;       const char* Ks = K_lds + buf * SHM_K;
; #pragma unroll
;       for (int d0 = 0; d0 < NQ; ++d0) { const int cb = kcolB + (d0 * 16 + hi * 8) * 2;
;         const bf16x8 k0 = *(const bf16x8*)(Ks + KSWZ(r32, cb)); const bf16x8 k1 = *(const bf16x8*)(Ks + KSWZ(32 + r32, cb));
;         p0 = __builtin_amdgcn_mfma_f32_32x32x16_bf16(k0, qr[d0], p0, 0, 0, 0);
;         p1 = __builtin_amdgcn_mfma_f32_32x32x16_bf16(k1, qr[d0], p1, 0, 0, 0); }
.LBB0_305:
	s_add_i32 s43, s0, -1
	s_and_b32 s44, s43, 1
	v_cmp_lt_u32_e32 vcc, s43, v177
	s_and_saveexec_b64 s[14:15], vcc
	s_cbranch_execz .LBB0_317
	v_cmp_gt_i32_e32 vcc, s42, v179
	s_and_saveexec_b64 s[16:17], vcc
	s_cbranch_execz .Latt1_far
	v_add_u32_e32 v98, s39, v155
	v_add_u32_e32 v84, 0x10dfc, v98
	v_add_u32_e32 v86, 0x10e7c, v98
	v_add_u32_e32 v87, 0x10e04, v98
	v_add_u32_e32 v88, 0x10e84, v98
	ds_read2_b32 v[84:85], v84 offset1:1
	ds_read2_b32 v[234:235], v86 offset1:1
	ds_read2_b32 v[86:87], v87 offset1:1
	ds_read2_b32 v[236:237], v88 offset1:1
	v_add_u32_e32 v88, 0x10e1c, v98
	v_add_u32_e32 v90, 0x10e9c, v98
	v_add_u32_e32 v91, 0x10e24, v98
	v_add_u32_e32 v92, 0x10ea4, v98
	ds_read2_b32 v[88:89], v88 offset1:1
	ds_read2_b32 v[238:239], v90 offset1:1
	ds_read2_b32 v[90:91], v91 offset1:1
	ds_read2_b32 v[240:241], v92 offset1:1
	v_add_u32_e32 v92, 0x10e3c, v98
	v_add_u32_e32 v94, 0x10ebc, v98
	v_add_u32_e32 v95, 0x10e44, v98
	v_add_u32_e32 v96, 0x10ec4, v98
	ds_read2_b32 v[92:93], v92 offset1:1
	ds_read2_b32 v[242:243], v94 offset1:1
	ds_read2_b32 v[94:95], v95 offset1:1
	ds_read2_b32 v[244:245], v96 offset1:1
	v_add_u32_e32 v99, 0x10e5c, v98
	v_add_u32_e32 v96, 0x10e64, v98
	v_add_u32_e32 v100, 0x10edc, v98
	ds_read2_b32 v[96:97], v96 offset1:1
	v_add_u32_e32 v101, 0x10ee4, v98
	ds_read2_b32 v[98:99], v99 offset1:1
	ds_read2_b32 v[246:247], v101 offset1:1
	ds_read2_b32 v[248:249], v100 offset1:1
	s_waitcnt lgkmcnt(5)
	v_sub_f32_e32 v111, v95, v231
	v_sub_f32_e32 v110, v94, v231
	s_waitcnt lgkmcnt(3)
	v_sub_f32_e32 v115, v97, v231
	v_sub_f32_e32 v114, v96, v231
	s_waitcnt lgkmcnt(2)
	v_sub_f32_e32 v113, v99, v231
	v_sub_f32_e32 v112, v98, v231
	v_sub_f32_e32 v109, v93, v231
	v_sub_f32_e32 v108, v92, v231
	v_sub_f32_e32 v107, v91, v231
	v_sub_f32_e32 v106, v90, v231
	v_sub_f32_e32 v105, v89, v231
	v_sub_f32_e32 v104, v88, v231
	v_sub_f32_e32 v103, v87, v231
	v_sub_f32_e32 v102, v86, v231
	v_sub_f32_e32 v101, v85, v231
	v_sub_f32_e32 v100, v84, v231
	s_waitcnt lgkmcnt(1)
	v_sub_f32_e32 v99, v247, v231
	v_sub_f32_e32 v98, v246, v231
	s_waitcnt lgkmcnt(0)
	v_sub_f32_e32 v97, v249, v231
	v_sub_f32_e32 v96, v248, v231
	v_sub_f32_e32 v95, v245, v231
	v_sub_f32_e32 v94, v244, v231
	v_sub_f32_e32 v93, v243, v231
	v_sub_f32_e32 v92, v242, v231
	v_sub_f32_e32 v91, v241, v231
	v_sub_f32_e32 v90, v240, v231
	v_sub_f32_e32 v89, v239, v231
	v_sub_f32_e32 v88, v238, v231
	v_sub_f32_e32 v87, v237, v231
	v_sub_f32_e32 v86, v236, v231
	v_sub_f32_e32 v85, v235, v231
	v_sub_f32_e32 v84, v234, v231
	s_branch .LBB0_308
.Latt1_far:
	s_or_b64 exec, exec, s[16:17]
	s_lshl_b32 s45, s44, 14
	v_add_u32_e32 v194, s45, v216
	v_add_u32_e32 v233, v194, v219
	ds_read_b128 v[234:237], v233 offset:32768
	ds_read_b128 v[238:241], v233 offset:40960
	v_add_u32_e32 v233, v194, v220
	s_waitcnt vmcnt(7) lgkmcnt(1)
	v_mfma_f32_32x32x16_bf16 v[100:115], v[234:237], v[116:119], v[68:83]
	s_waitcnt lgkmcnt(0)
	v_mfma_f32_32x32x16_bf16 v[84:99], v[238:241], v[116:119], v[68:83]
	s_branch .Latt1_join

; template <int MODE>
; __device__ __forceinline__ void attn_unit(const AttnP& P, int b, int h, int u, int j0, char* lds, float lam) {
;     ...
;       for (int d0 = 0; d0 < NQ; ++d0) { const int cb = kcolB + (d0 * 16 + hi * 8) * 2;
;         const bf16x8 k0 = *(const bf16x8*)(Ks + KSWZ(r32, cb)); const bf16x8 k1 = *(const bf16x8*)(Ks + KSWZ(32 + r32, cb));
;         p0 = __builtin_amdgcn_mfma_f32_32x32x16_bf16(k0, qr[d0], p0, 0, 0, 0);
;         p1 = __builtin_amdgcn_mfma_f32_32x32x16_bf16(k1, qr[d0], p1, 0, 0, 0); }
.Latt1_join:
	ds_read_b128 v[234:237], v233 offset:32768
	ds_read_b128 v[238:241], v233 offset:40960
	v_add_u32_e32 v233, v194, v221
	v_add_u32_e32 v194, v194, v222
	s_waitcnt vmcnt(6) lgkmcnt(1)
	v_mfma_f32_32x32x16_bf16 v[100:115], v[234:237], v[120:123], v[100:115]
	s_waitcnt lgkmcnt(0)
	v_mfma_f32_32x32x16_bf16 v[84:99], v[238:241], v[120:123], v[84:99]
	ds_read_b128 v[234:237], v233 offset:32768
	ds_read_b128 v[238:241], v233 offset:40960
	s_waitcnt vmcnt(5) lgkmcnt(1)
	v_mfma_f32_32x32x16_bf16 v[100:115], v[234:237], v[124:127], v[100:115]
	s_waitcnt lgkmcnt(0)
	v_mfma_f32_32x32x16_bf16 v[84:99], v[238:241], v[124:127], v[84:99]
	ds_read_b128 v[234:237], v194 offset:32768
	ds_read_b128 v[238:241], v194 offset:40960
	s_waitcnt vmcnt(4) lgkmcnt(1)
	v_mfma_f32_32x32x16_bf16 v[100:115], v[234:237], v[132:135], v[100:115]
	s_waitcnt lgkmcnt(0)
	v_mfma_f32_32x32x16_bf16 v[84:99], v[238:241], v[132:135], v[84:99]
	s_nop 9
	v_max_f32_e32 v194, v101, v101
	v_max_f32_e32 v233, v100, v100
	v_max_f32_e32 v194, v233, v194
	v_max3_f32 v194, v194, v102, v103
	v_max3_f32 v194, v194, v104, v105
	v_max3_f32 v194, v194, v106, v107
	v_max3_f32 v194, v194, v108, v109
	v_max3_f32 v194, v194, v110, v111
	v_max3_f32 v194, v194, v112, v113
	v_max3_f32 v194, v194, v114, v115
	v_mov_b32_e32 v233, v194
	s_nop 1
	v_permlane32_swap_b32_e32 v194, v233
	v_max_f32_e32 v233, v233, v233
	v_max_f32_e32 v194, v194, v194
	v_max_f32_e32 v194, v194, v233
	v_cmp_lt_f32_e32 vcc, s26, v194
	s_cbranch_vccz .LBB0_312
	v_max_f32_e32 v194, v194, v194
	v_max_f32_e32 v194, 0, v194
	v_exp_f32_e64 v233, -v194
	s_and_saveexec_b64 s[16:17], s[2:3]
	ds_write_b32 v218, v233 offset:128
	s_or_b64 exec, exec, s[16:17]
	v_pk_add_f32 v[100:101], v[100:101], v[194:195] op_sel_hi:[1,0] neg_lo:[0,1] neg_hi:[0,1]
	v_pk_add_f32 v[102:103], v[102:103], v[194:195] op_sel_hi:[1,0] neg_lo:[0,1] neg_hi:[0,1]
	v_pk_add_f32 v[104:105], v[104:105], v[194:195] op_sel_hi:[1,0] neg_lo:[0,1] neg_hi:[0,1]
	v_pk_add_f32 v[106:107], v[106:107], v[194:195] op_sel_hi:[1,0] neg_lo:[0,1] neg_hi:[0,1]
	v_pk_add_f32 v[108:109], v[108:109], v[194:195] op_sel_hi:[1,0] neg_lo:[0,1] neg_hi:[0,1]
	v_pk_add_f32 v[110:111], v[110:111], v[194:195] op_sel_hi:[1,0] neg_lo:[0,1] neg_hi:[0,1]
	v_pk_add_f32 v[112:113], v[112:113], v[194:195] op_sel_hi:[1,0] neg_lo:[0,1] neg_hi:[0,1]
	v_pk_add_f32 v[114:115], v[114:115], v[194:195] op_sel_hi:[1,0] neg_lo:[0,1] neg_hi:[0,1]
	v_sub_f32_e32 v99, v99, v194
	v_sub_f32_e32 v98, v98, v194
	v_sub_f32_e32 v97, v97, v194
	v_sub_f32_e32 v96, v96, v194
	v_sub_f32_e32 v95, v95, v194
	v_sub_f32_e32 v94, v94, v194
	v_sub_f32_e32 v93, v93, v194
	v_sub_f32_e32 v92, v92, v194
	v_sub_f32_e32 v91, v91, v194
	v_sub_f32_e32 v90, v90, v194
	v_sub_f32_e32 v89, v89, v194
	v_sub_f32_e32 v88, v88, v194
	v_sub_f32_e32 v87, v87, v194
	v_sub_f32_e32 v86, v86, v194
	v_sub_f32_e32 v85, v85, v194
	v_sub_f32_e32 v84, v84, v194
	v_sub_f32_e32 v83, v83, v194
	v_sub_f32_e32 v82, v82, v194
	v_sub_f32_e32 v81, v81, v194
	v_sub_f32_e32 v80, v80, v194
	v_sub_f32_e32 v79, v79, v194
	v_sub_f32_e32 v78, v78, v194
	v_sub_f32_e32 v77, v77, v194
	v_sub_f32_e32 v76, v76, v194
	v_sub_f32_e32 v75, v75, v194
	v_sub_f32_e32 v74, v74, v194
	v_sub_f32_e32 v73, v73, v194
	v_sub_f32_e32 v72, v72, v194
	v_sub_f32_e32 v71, v71, v194
	v_sub_f32_e32 v70, v70, v194
	v_sub_f32_e32 v69, v69, v194
	v_sub_f32_e32 v68, v68, v194
	v_add_f32_e32 v231, v231, v194
	s_waitcnt lgkmcnt(0)
	v_add_u32_e32 v194, v210, v215
	ds_read_b128 v[234:237], v194 offset:128
	ds_read_b128 v[238:241], v194 offset:160
	ds_read_b128 v[242:245], v194 offset:192
	ds_read_b128 v[246:249], v194 offset:224
	v_mul_f32_e32 v232, v232, v233
	s_waitcnt lgkmcnt(3)
	v_pk_mul_f32 v[6:7], v[6:7], v[236:237]
	s_waitcnt lgkmcnt(2)
	v_pk_mul_f32 v[8:9], v[8:9], v[238:239]
	s_waitcnt lgkmcnt(1)
	v_pk_mul_f32 v[12:13], v[12:13], v[242:243]
	s_waitcnt lgkmcnt(0)
	v_pk_mul_f32 v[16:17], v[16:17], v[246:247]
	v_pk_mul_f32 v[18:19], v[18:19], v[248:249]
	v_pk_mul_f32 v[14:15], v[14:15], v[244:245]
	v_pk_mul_f32 v[10:11], v[10:11], v[240:241]
	v_pk_mul_f32 v[4:5], v[4:5], v[234:235]
	v_pk_mul_f32 v[64:65], v[64:65], v[246:247]
	v_pk_mul_f32 v[60:61], v[60:61], v[242:243]
	v_pk_mul_f32 v[56:57], v[56:57], v[238:239]
	v_pk_mul_f32 v[66:67], v[66:67], v[248:249]
	v_pk_mul_f32 v[62:63], v[62:63], v[244:245]
	v_pk_mul_f32 v[58:59], v[58:59], v[240:241]
	v_pk_mul_f32 v[54:55], v[54:55], v[236:237]
	v_pk_mul_f32 v[52:53], v[52:53], v[234:235]
	v_pk_mul_f32 v[32:33], v[32:33], v[246:247]
	v_pk_mul_f32 v[28:29], v[28:29], v[242:243]
	v_pk_mul_f32 v[24:25], v[24:25], v[238:239]
	v_pk_mul_f32 v[34:35], v[34:35], v[248:249]
	v_pk_mul_f32 v[30:31], v[30:31], v[244:245]
	v_pk_mul_f32 v[26:27], v[26:27], v[240:241]
	v_pk_mul_f32 v[22:23], v[22:23], v[236:237]
	v_pk_mul_f32 v[20:21], v[20:21], v[234:235]
	v_pk_mul_f32 v[48:49], v[48:49], v[246:247]
	v_pk_mul_f32 v[44:45], v[44:45], v[242:243]
	v_pk_mul_f32 v[40:41], v[40:41], v[238:239]
	v_pk_mul_f32 v[50:51], v[50:51], v[248:249]
	v_pk_mul_f32 v[46:47], v[46:47], v[244:245]
	v_pk_mul_f32 v[42:43], v[42:43], v[240:241]
	v_pk_mul_f32 v[38:39], v[38:39], v[236:237]
	v_pk_mul_f32 v[36:37], v[36:37], v[234:235]

; __device__ __forceinline__ int crow(int r, int hi) { return (r & 3) + 8 * (r >> 2) + 4 * hi; }
; template <int MODE>
; __device__ __forceinline__ void attn_unit(const AttnP& P, int b, int h, int u, int j0, char* lds, float lam) {
;     ...
;       const bool far = (MODE == 0) && (j * 64 + 63 <= qw - 128);
;       if (far) { p0 = negm; p1 = negm; }
;       else if (MODE == 0) { const int idx0 = j * 64 - (qw + r32) + 255;
; #pragma unroll
;         for (int r = 0; r < 16; ++r) { p0[r] = lut[idx0 + crow(r, hi)] - mref; p1[r] = lut[idx0 + 32 + crow(r, hi)] - mref; }
;       } else {
; #pragma unroll
;         for (int r = 0; r < 16; ++r) { p0[r] = Gl[j * 64 + crow(r, hi)] - mref; p1[r] = Gl[j * 64 + 32 + crow(r, hi)] - mref; }
;       }
;       const char* Ks = K_lds + buf * SHM_K;
; #pragma unroll
;       for (int d0 = 0; d0 < NQ; ++d0) { const int cb = kcolB + (d0 * 16 + hi * 8) * 2;
;         const bf16x8 k0 = *(const bf16x8*)(Ks + KSWZ(r32, cb)); const bf16x8 k1 = *(const bf16x8*)(Ks + KSWZ(32 + r32, cb));
;         p0 = __builtin_amdgcn_mfma_f32_32x32x16_bf16(k0, qr[d0], p0, 0, 0, 0);
;         p1 = __builtin_amdgcn_mfma_f32_32x32x16_bf16(k1, qr[d0], p1, 0, 0, 0); }
.LBB0_324:
	s_add_i32 s37, s17, -1
	s_and_b32 s38, s37, 1
	v_cmp_lt_u32_e32 vcc, s37, v188
	s_and_saveexec_b64 s[12:13], vcc
	s_cbranch_execz .LBB0_336
	v_cmp_gt_u32_e32 vcc, s30, v190
	s_and_saveexec_b64 s[14:15], vcc
	s_cbranch_execz .Latt2_far
	v_add_u32_e32 v2, s31, v189
	v_add_u32_e32 v5, 0x10dfc, v2
	v_add_u32_e32 v8, 0x10e7c, v2
	v_add_u32_e32 v10, 0x10e04, v2
	v_add_u32_e32 v12, 0x10e84, v2
	ds_read2_b32 v[6:7], v5 offset1:1
	ds_read2_b32 v[8:9], v8 offset1:1
	ds_read2_b32 v[10:11], v10 offset1:1
	ds_read2_b32 v[12:13], v12 offset1:1
	v_add_u32_e32 v5, 0x10e1c, v2
	v_add_u32_e32 v16, 0x10e9c, v2
	v_add_u32_e32 v98, 0x10e24, v2
	v_add_u32_e32 v100, 0x10ea4, v2
	ds_read2_b32 v[14:15], v5 offset1:1
	ds_read2_b32 v[16:17], v16 offset1:1
	ds_read2_b32 v[98:99], v98 offset1:1
	ds_read2_b32 v[100:101], v100 offset1:1
	v_add_u32_e32 v5, 0x10e3c, v2
	v_add_u32_e32 v104, 0x10ebc, v2
	v_add_u32_e32 v106, 0x10e44, v2
	v_add_u32_e32 v108, 0x10ec4, v2
	ds_read2_b32 v[102:103], v5 offset1:1
	ds_read2_b32 v[104:105], v104 offset1:1
	ds_read2_b32 v[106:107], v106 offset1:1
	ds_read2_b32 v[108:109], v108 offset1:1
	v_add_u32_e32 v5, 0x10e5c, v2
	v_add_u32_e32 v110, 0x10e64, v2
	v_add_u32_e32 v114, 0x10edc, v2
	ds_read2_b32 v[110:111], v110 offset1:1
	v_add_u32_e32 v2, 0x10ee4, v2
	ds_read2_b32 v[112:113], v5 offset1:1
	ds_read2_b32 v[238:239], v2 offset1:1
	ds_read2_b32 v[240:241], v114 offset1:1
	s_waitcnt lgkmcnt(5)
	v_sub_f32_e32 v125, v107, v179
	v_sub_f32_e32 v124, v106, v179
	s_waitcnt lgkmcnt(3)
	v_sub_f32_e32 v129, v111, v179
	v_sub_f32_e32 v128, v110, v179
	s_waitcnt lgkmcnt(2)
	v_sub_f32_e32 v127, v113, v179
	v_sub_f32_e32 v126, v112, v179
	v_sub_f32_e32 v123, v103, v179
	v_sub_f32_e32 v122, v102, v179
	v_sub_f32_e32 v121, v99, v179
	v_sub_f32_e32 v120, v98, v179
	v_sub_f32_e32 v119, v15, v179
	v_sub_f32_e32 v118, v14, v179
	v_sub_f32_e32 v117, v11, v179
	v_sub_f32_e32 v116, v10, v179
	v_sub_f32_e32 v115, v7, v179
	v_sub_f32_e32 v114, v6, v179
	s_waitcnt lgkmcnt(1)
	v_sub_f32_e32 v113, v239, v179
	v_sub_f32_e32 v112, v238, v179
	s_waitcnt lgkmcnt(0)
	v_sub_f32_e32 v111, v241, v179
	v_sub_f32_e32 v110, v240, v179
	v_sub_f32_e32 v109, v109, v179
	v_sub_f32_e32 v108, v108, v179
	v_sub_f32_e32 v107, v105, v179
	v_sub_f32_e32 v106, v104, v179
	v_sub_f32_e32 v105, v101, v179
	v_sub_f32_e32 v104, v100, v179
	v_sub_f32_e32 v103, v17, v179
	v_sub_f32_e32 v102, v16, v179
	v_sub_f32_e32 v101, v13, v179
	v_sub_f32_e32 v100, v12, v179
	v_sub_f32_e32 v99, v9, v179
	v_sub_f32_e32 v98, v8, v179
	s_branch .LBB0_327
.Latt2_far:
	s_or_b64 exec, exec, s[14:15]
	s_lshl_b32 s39, s38, 14
	v_add_u32_e32 v2, s39, v216
	v_add_u32_e32 v5, v2, v219
	ds_read_b128 v[6:9], v5 offset:32768
	ds_read_b128 v[10:13], v5 offset:40960
	v_add_u32_e32 v5, v2, v220
	s_waitcnt vmcnt(7) lgkmcnt(1)
	v_mfma_f32_32x32x16_bf16 v[114:129], v[6:9], v[132:135], v[82:97]
	s_waitcnt lgkmcnt(0)
	v_mfma_f32_32x32x16_bf16 v[98:113], v[10:13], v[132:135], v[82:97]
	s_branch .Latt2_join

; template <int MODE>
; __device__ __forceinline__ void attn_unit(const AttnP& P, int b, int h, int u, int j0, char* lds, float lam) {
;     ...
;       for (int d0 = 0; d0 < NQ; ++d0) { const int cb = kcolB + (d0 * 16 + hi * 8) * 2;
;         const bf16x8 k0 = *(const bf16x8*)(Ks + KSWZ(r32, cb)); const bf16x8 k1 = *(const bf16x8*)(Ks + KSWZ(32 + r32, cb));
;         p0 = __builtin_amdgcn_mfma_f32_32x32x16_bf16(k0, qr[d0], p0, 0, 0, 0);
;         p1 = __builtin_amdgcn_mfma_f32_32x32x16_bf16(k1, qr[d0], p1, 0, 0, 0); }
.Latt2_join:
	ds_read_b128 v[6:9], v5 offset:32768
	ds_read_b128 v[10:13], v5 offset:40960
	v_add_u32_e32 v5, v2, v221
	v_add_u32_e32 v2, v2, v222
	s_waitcnt vmcnt(6) lgkmcnt(1)
	v_mfma_f32_32x32x16_bf16 v[114:129], v[6:9], v[136:139], v[114:129]
	s_waitcnt lgkmcnt(0)
	v_mfma_f32_32x32x16_bf16 v[98:113], v[10:13], v[136:139], v[98:113]
	ds_read_b128 v[6:9], v5 offset:32768
	ds_read_b128 v[10:13], v5 offset:40960
	s_waitcnt vmcnt(5) lgkmcnt(1)
	v_mfma_f32_32x32x16_bf16 v[114:129], v[6:9], v[140:143], v[114:129]
	s_waitcnt lgkmcnt(0)
	v_mfma_f32_32x32x16_bf16 v[98:113], v[10:13], v[140:143], v[98:113]
	ds_read_b128 v[6:9], v2 offset:32768
	ds_read_b128 v[10:13], v2 offset:40960
	s_waitcnt vmcnt(4) lgkmcnt(1)
	v_mfma_f32_32x32x16_bf16 v[114:129], v[6:9], v[144:147], v[114:129]
	s_waitcnt lgkmcnt(0)
	v_mfma_f32_32x32x16_bf16 v[98:113], v[10:13], v[144:147], v[98:113]
	s_nop 9
	v_max_f32_e32 v2, v115, v115
	v_max_f32_e32 v5, v114, v114
	v_max_f32_e32 v2, v5, v2
	v_max3_f32 v2, v2, v116, v117
	v_max3_f32 v2, v2, v118, v119
	v_max3_f32 v2, v2, v120, v121
	v_max3_f32 v2, v2, v122, v123
	v_max3_f32 v2, v2, v124, v125
	v_max3_f32 v2, v2, v126, v127
	v_max3_f32 v2, v2, v128, v129
	v_mov_b32_e32 v5, v2
	s_nop 1
	v_permlane32_swap_b32_e32 v2, v5
	v_max_f32_e32 v5, v5, v5
	v_max_f32_e32 v2, v2, v2
	v_max_f32_e32 v2, v2, v5
	v_cmp_lt_f32_e32 vcc, s26, v2
	s_cbranch_vccz .LBB0_331
	v_max_f32_e32 v2, v2, v2
	v_max_f32_e32 v2, 0, v2
	v_exp_f32_e64 v5, -v2
	s_and_saveexec_b64 s[14:15], s[2:3]
	ds_write_b32 v218, v5 offset:128
	s_or_b64 exec, exec, s[14:15]
	s_waitcnt lgkmcnt(0)
	ds_read_b128 v[6:9], v192 offset:128
	ds_read_b128 v[10:13], v192 offset:160
	ds_read_b128 v[14:17], v192 offset:192
	ds_read_b128 v[238:241], v192 offset:224
	v_pk_add_f32 v[114:115], v[114:115], v[2:3] op_sel_hi:[1,0] neg_lo:[0,1] neg_hi:[0,1]
	v_pk_add_f32 v[116:117], v[116:117], v[2:3] op_sel_hi:[1,0] neg_lo:[0,1] neg_hi:[0,1]
	v_pk_add_f32 v[118:119], v[118:119], v[2:3] op_sel_hi:[1,0] neg_lo:[0,1] neg_hi:[0,1]
	v_pk_add_f32 v[120:121], v[120:121], v[2:3] op_sel_hi:[1,0] neg_lo:[0,1] neg_hi:[0,1]
	v_pk_add_f32 v[122:123], v[122:123], v[2:3] op_sel_hi:[1,0] neg_lo:[0,1] neg_hi:[0,1]
	v_pk_add_f32 v[124:125], v[124:125], v[2:3] op_sel_hi:[1,0] neg_lo:[0,1] neg_hi:[0,1]
	v_pk_add_f32 v[126:127], v[126:127], v[2:3] op_sel_hi:[1,0] neg_lo:[0,1] neg_hi:[0,1]
	v_pk_add_f32 v[128:129], v[128:129], v[2:3] op_sel_hi:[1,0] neg_lo:[0,1] neg_hi:[0,1]
	v_sub_f32_e32 v113, v113, v2
	v_sub_f32_e32 v112, v112, v2
	v_sub_f32_e32 v111, v111, v2
	v_sub_f32_e32 v110, v110, v2
	v_sub_f32_e32 v109, v109, v2
	v_sub_f32_e32 v108, v108, v2
	v_sub_f32_e32 v107, v107, v2
	v_sub_f32_e32 v106, v106, v2
	v_sub_f32_e32 v105, v105, v2
	v_sub_f32_e32 v104, v104, v2
	v_sub_f32_e32 v103, v103, v2
	v_sub_f32_e32 v102, v102, v2
	v_sub_f32_e32 v101, v101, v2
	v_sub_f32_e32 v100, v100, v2
	v_sub_f32_e32 v99, v99, v2
	v_sub_f32_e32 v98, v98, v2
	v_sub_f32_e32 v97, v97, v2
	v_sub_f32_e32 v96, v96, v2
	v_sub_f32_e32 v95, v95, v2
	v_sub_f32_e32 v94, v94, v2
	v_sub_f32_e32 v93, v93, v2
	v_sub_f32_e32 v92, v92, v2
	v_sub_f32_e32 v91, v91, v2
	v_sub_f32_e32 v90, v90, v2
	v_sub_f32_e32 v89, v89, v2
	v_sub_f32_e32 v88, v88, v2
	v_sub_f32_e32 v87, v87, v2
	v_sub_f32_e32 v86, v86, v2
	v_sub_f32_e32 v85, v85, v2
	v_sub_f32_e32 v84, v84, v2
	v_sub_f32_e32 v83, v83, v2
	v_sub_f32_e32 v82, v82, v2
	v_add_f32_e32 v179, v179, v2
	v_mul_f32_e32 v4, v4, v5
	s_waitcnt lgkmcnt(0)
	v_pk_mul_f32 v[62:63], v[62:63], v[238:239]
	v_pk_mul_f32 v[58:59], v[58:59], v[14:15]
	v_pk_mul_f32 v[54:55], v[54:55], v[10:11]
	v_pk_mul_f32 v[64:65], v[64:65], v[240:241]
	v_pk_mul_f32 v[60:61], v[60:61], v[16:17]
	v_pk_mul_f32 v[56:57], v[56:57], v[12:13]
	v_pk_mul_f32 v[52:53], v[52:53], v[8:9]
	v_pk_mul_f32 v[50:51], v[50:51], v[6:7]
	v_pk_mul_f32 v[78:79], v[78:79], v[238:239]
	v_pk_mul_f32 v[74:75], v[74:75], v[14:15]
	v_pk_mul_f32 v[70:71], v[70:71], v[10:11]
	v_pk_mul_f32 v[80:81], v[80:81], v[240:241]
	v_pk_mul_f32 v[76:77], v[76:77], v[16:17]
	v_pk_mul_f32 v[72:73], v[72:73], v[12:13]
	v_pk_mul_f32 v[68:69], v[68:69], v[8:9]
	v_pk_mul_f32 v[66:67], v[66:67], v[6:7]
	v_pk_mul_f32 v[30:31], v[30:31], v[238:239]
	v_pk_mul_f32 v[26:27], v[26:27], v[14:15]
	v_pk_mul_f32 v[22:23], v[22:23], v[10:11]
	v_pk_mul_f32 v[32:33], v[32:33], v[240:241]
	v_pk_mul_f32 v[28:29], v[28:29], v[16:17]
	v_pk_mul_f32 v[24:25], v[24:25], v[12:13]
	v_pk_mul_f32 v[20:21], v[20:21], v[8:9]
	v_pk_mul_f32 v[18:19], v[18:19], v[6:7]
	v_pk_mul_f32 v[46:47], v[46:47], v[238:239]
	v_pk_mul_f32 v[42:43], v[42:43], v[14:15]
	v_pk_mul_f32 v[38:39], v[38:39], v[10:11]
	v_pk_mul_f32 v[48:49], v[48:49], v[240:241]
	v_pk_mul_f32 v[44:45], v[44:45], v[16:17]
	v_pk_mul_f32 v[40:41], v[40:41], v[12:13]
	v_pk_mul_f32 v[36:37], v[36:37], v[8:9]
	v_pk_mul_f32 v[34:35], v[34:35], v[6:7]
